# grid barrier: waiting workgroups poll the top-level generation word directly (skips the per-XCD generation hop)
# speedup vs baseline: 1.0019x; 1.0019x over previous
.LBB0_1347:
	s_or_b64 exec, exec, s[6:7]
	v_cvt_f32_u32_e32 v5, v3
	s_waitcnt vmcnt(0)
	v_readfirstlane_b32 s4, v4
	v_sub_u32_e32 v4, 0, v3
	v_rcp_iflag_f32_e32 v5, v5
	v_add_u32_e32 v6, s4, v1
	v_mul_f32_e32 v5, 0x4f7ffffe, v5
	v_cvt_u32_f32_e32 v5, v5
	v_mul_lo_u32 v1, v4, v5
	v_mul_hi_u32 v1, v5, v1
	v_add_u32_e32 v1, v5, v1
	v_mul_hi_u32 v1, v6, v1
	v_mul_lo_u32 v4, v1, v3
	v_sub_u32_e32 v4, v6, v4
	v_add_u32_e32 v5, 1, v1
	v_cmp_ge_u32_e32 vcc, v4, v3
	s_nop 1
	v_cndmask_b32_e32 v1, v1, v5, vcc
	v_sub_u32_e32 v5, v4, v3
	v_cndmask_b32_e32 v4, v4, v5, vcc
	v_add_u32_e32 v5, 1, v1
	v_cmp_ge_u32_e32 vcc, v4, v3
	v_add_u32_e32 v4, 1, v6
	s_nop 0
	v_cndmask_b32_e32 v1, v1, v5, vcc
	v_mul_lo_u32 v5, v3, v1
	v_add_u32_e32 v3, v5, v3
	v_cmp_ne_u32_e32 vcc, v4, v3
	s_and_saveexec_b64 s[4:5], vcc
	s_xor_b64 s[4:5], exec, s[4:5]
	s_cbranch_execz .LBB0_1361
	s_waitcnt lgkmcnt(0)
	v_readlane_b32 s8, v254, 8
	v_readlane_b32 s9, v254, 9
	s_nop 4
	global_load_dword v2, v26, s[8:9] sc1
	s_waitcnt vmcnt(0)
	v_cmp_eq_u32_e32 vcc, v2, v1
	s_and_saveexec_b64 s[6:7], vcc
	s_cbranch_execz .LBB0_1360
	s_mov_b32 s24, 1
	s_mov_b64 s[10:11], 0
	s_branch .LBB0_1351
